# sample conv/qk-prep/hgrn1 phase: static items rebalanced (qk-prep blocks drop their conv item, light blocks take it)
# speedup vs baseline: 1.0058x; 1.0058x over previous
.LBB0_309:
	s_andn2_b64 vcc, exec, s[4:5]
	s_cbranch_vccnz .LBB0_506
	s_add_i32 s4, s6, 18
	s_cmp_lt_u32 s4, 39
	s_cselect_b64 s[38:39], -1, 0
	s_cmp_gt_u32 s4, 38
	s_cselect_b64 s[4:5], -1, 0
	v_writelane_b32 v255, s4, 4
	s_mov_b32 s20, s22
	s_nop 0
	v_writelane_b32 v255, s5, 5
	v_readlane_b32 s4, v254, 63
	v_readlane_b32 s5, v255, 0
	v_writelane_b32 v255, s20, 2
	s_andn2_b64 vcc, exec, s[4:5]
	s_mov_b64 s[4:5], -1
	v_writelane_b32 v255, s21, 3
	s_cbranch_vccnz .LBB0_408
	s_cmpk_gt_i32 s71, 0x387
	s_cbranch_scc1 .LBB0_407
	v_readlane_b32 s4, v254, 62
	s_lshl_b32 s49, s4, 8
	v_readlane_b32 s4, v255, 2
	v_readlane_b32 s5, v255, 3
	s_mov_b32 s20, s4
	s_lshl_b32 s40, s4, 6
	v_readlane_b32 s52, v253, 8
	s_ashr_i32 s41, s40, 31
	s_mul_i32 s5, s20, 0xf800
	v_readlane_b32 s56, v253, 12
	s_mul_hi_i32 s4, s4, 0xf800
	v_readlane_b32 s57, v253, 13
	s_add_u32 s50, s56, s5
	s_addc_u32 s51, s57, s4
	s_lshl_b32 s4, s20, 9
	s_ashr_i32 s5, s4, 31
	v_readlane_b32 s58, v253, 14
	s_lshl_b64 s[4:5], s[4:5], 2
	v_readlane_b32 s59, v253, 15
	s_add_u32 s72, s58, s4
	v_readlane_b32 s60, v253, 16
	s_addc_u32 s73, s59, s5
	v_readlane_b32 s61, v253, 17
	s_add_u32 s36, s60, s4
	v_readlane_b32 s62, v253, 18
	s_addc_u32 s37, s61, s5
	v_readlane_b32 s63, v253, 19
	s_add_u32 s22, s62, s4
	s_mov_b32 s75, 0x60000
	s_mov_b32 s76, 0x8000
	s_addc_u32 s23, s63, s5
	s_mov_b32 s4, s71
	s_cmpk_eq_u32 s81, 0x200
	s_cbranch_scc0 .Lk2_e
	s_cmpk_lt_u32 s71, 0x100
	s_cbranch_scc1 .Lk2_e
	s_cmpk_ge_u32 s71, 0x188
	s_cbranch_scc1 .Lk2_e
	s_add_u32 s4, s71, 0x200
.Lk2_e:
	v_readlane_b32 s53, v253, 9
	v_readlane_b32 s54, v253, 10
	v_readlane_b32 s55, v253, 11
	v_readlane_b32 s64, v253, 20
	v_readlane_b32 s65, v253, 21
	v_readlane_b32 s66, v253, 22
	v_readlane_b32 s67, v253, 23
	s_branch .LBB0_315

.LBB0_314:
	s_cmpk_eq_u32 s81, 0x200
	s_cbranch_scc0 .Lk2_orig
	s_cmpk_lt_u32 s71, 0x188
	s_cbranch_scc1 .Lk2_orig
	s_cmp_eq_u32 s4, s71
	s_cbranch_scc0 .Lk2_z2
	s_sub_u32 s4, s71, 0x88
	s_branch .LBB0_315
.Lk2_z2:
	s_sub_u32 s98, s71, 0x88
	s_cmp_eq_u32 s4, s98
	s_cbranch_scc0 .LBB0_407
	s_cmpk_ge_u32 s71, 0x198
	s_cbranch_scc1 .LBB0_407
	s_sub_u32 s4, s71, 16
	s_branch .LBB0_315
